# UP K-loop: the first two counted vmcnt waits of the first iteration after an epilogue allow the epilogue's 16 younger stores to stay in flight (vmcnt 8 -> 24)
# speedup vs baseline: 1.0005x; 1.0005x over previous
; #define PG8_BAR __builtin_amdgcn_s_barrier()
; template <class Epi, class Sched, bool ALIGN_EPI = false, bool SP2 = false>
; __device__ __forceinline__ void gemm_phase(PG8_LAS unsigned char* lds, const Gemm g, const Sched& S, const Epi& E) {
;     int tid_ = threadIdx.x; asm volatile("" : "+v"(tid_));
;     const int tid = tid_, wid = __builtin_amdgcn_readfirstlane(tid >> 6), lane = tid & 63, wr = wid >> 2, wc = wid & 3, fr = lane & 15, fq = lane >> 4;
;     const int K = g.K, nt = K / BK, LD = g.ld ? g.ld : g.K;
;     unsigned voffA[2], voffB[2];
; #pragma unroll
;     for (int i = 0; i < 2; ++i) { int R, C; stage_rc(tid * 16 + i * 8192, R, C); const int Rb = Epi::PERM ? ((R & ~31) + perm32(R & 31)) : R;
;         voffA[i] = (unsigned)(R * LD + C) * 2u; voffB[i] = (unsigned)(Rb * LD + C) * 2u; }
;     const size_t kstep = (size_t)(BK * 2);
;     const size_t hstep = (size_t)HALF * LD * 2;
;     const size_t tstep = 2 * hstep;
;     const unsigned ldsw = (unsigned)wid * 1024u;
;     const int aoff = lds_byte(wr * 64 + fr, fq * 8), boff = lds_byte(wc * 32 + fr, fq * 8);
;     ...
;     Unit cur, nxt; int ui = 0;
;     if (!S.next(0, cur)) return;
;     f32x4 acc[2][2][4][2];
; #pragma unroll
;     for (int a = 0; a < 2; ++a)
; #pragma unroll
;         for (int b = 0; b < 2; ++b)
; #pragma unroll
;             for (int m = 0; m < 4; ++m)
; #pragma unroll
;                 for (int n = 0; n < 2; ++n) acc[a][b][m][n] = (f32x4){0.f, 0.f, 0.f, 0.f};
;     bf16x8 At[4][2], B0[2][2], B1[2][2];
;     const long rowb = (long)LD * 2;
;     const char* cA = (const char*)g.A + S.arow(cur.pm) * rowb; const char* cB = (const char*)g.Bt + (size_t)cur.pn * tstep;
;     S.a_ready(cur);
;     if constexpr (SP2) {
;         PG8_STAGE(PG8_SB(0, 0), cB, voffB); PG8_STAGE(PG8_SB(0, 1), cB + hstep, voffB); PG8_STAGE(PG8_SA(0, 0), cA, voffA); PG8_STAGE(PG8_SA(0, 1), cA + hstep, voffA);
;         if (wr == 1) PG8_BAR;
;         PG8_WAIT_V(2); PG8_BAR;
;         PG8_STAGE(PG8_SB(1, 0), cB + kstep, voffB); PG8_STAGE(PG8_SA(1, 0), cA + kstep, voffA); PG8_STAGE(PG8_SB(1, 1), cB + hstep + kstep, voffB);
;         PG8_WAIT_V(6); PG8_BAR;
;     } else {
;         PG8_STAGE(PG8_SB(0, 0), cB, voffB); PG8_STAGE(PG8_SA(0, 0), cA, voffA); PG8_STAGE(PG8_SB(0, 1), cB + hstep, voffB); PG8_STAGE(PG8_SA(0, 1), cA + hstep, voffA);
;         if (wr == 1) PG8_BAR;
;         PG8_WAIT_V(4); PG8_BAR;
.LBB0_685:
	v_readlane_b32 s0, v254, 27
	s_mov_b32 s16, s0
	s_mul_i32 s0, s0, 0x10800
	s_add_u32 s62, s8, s0
	s_addc_u32 s63, s7, 0
	s_mul_i32 s0, s16, 0x5800
	s_add_u32 s64, s14, s0
	s_addc_u32 s65, s9, 0
	s_add_u32 s66, s62, 0x5800
	s_addc_u32 s67, s63, 0
	s_add_u32 s68, s62, 0xb000
	s_addc_u32 s69, s63, 0
	s_and_b32 s3, s4, 3
	s_add_i32 m0, s80, 0x18000
	v_lshl_add_u64 v[6:7], v[6:7], 0, s[70:71]
	s_lshl_b32 s4, s15, 13
	s_lshl_b32 s5, s3, 12
	s_waitcnt vmcnt(2)
	s_barrier
	global_load_lds_dwordx4 v[6:7], off
	v_lshl_add_u64 v[4:5], v[4:5], 0, s[70:71]
	s_add_i32 m0, s80, 0x1a000
	s_add_i32 s82, s80, 0x8000
	s_add_i32 s83, s80, 0xa000
	v_readlane_b32 s1, v254, 28
	global_load_lds_dwordx4 v[4:5], off
	v_lshl_add_u64 v[2:3], v[2:3], 0, s[70:71]
	s_mov_b32 m0, s82
	s_add_u32 s0, s10, 0x40080
	global_load_lds_dwordx4 v[2:3], off
	v_lshl_add_u64 v[2:3], v[8:9], 0, s[70:71]
	s_mov_b32 m0, s83
	s_addc_u32 s1, s11, 0
	global_load_lds_dwordx4 v[2:3], off
	s_add_i32 m0, s80, 0x1c000
	v_lshl_add_u64 v[2:3], s[0:1], 0, v[34:35]
	global_load_lds_dwordx4 v[2:3], off
	v_lshl_add_u64 v[2:3], s[0:1], 0, v[188:189]
	s_add_i32 m0, s80, 0x1e000
	v_readlane_b32 s0, v255, 5
	global_load_lds_dwordx4 v[2:3], off
	v_readlane_b32 s1, v255, 6
	s_mov_b32 s1, s79
	v_writelane_b32 v255, s0, 5
	s_cmpk_lt_u32 s6, 0x100
	v_bfe_u32 v2, v10, 4, 2
	v_writelane_b32 v255, s1, 6
	s_cselect_b64 s[0:1], -1, 0
	v_writelane_b32 v255, s0, 13
	v_and_b32_e32 v226, 15, v10
	v_lshlrev_b32_e32 v3, 3, v2
	v_writelane_b32 v255, s1, 14
	s_lshl_b32 s0, s3, 2
	s_lshl_b32 s1, s15, 5
	v_lshlrev_b32_e32 v4, 4, v2
	v_lshlrev_b32_e32 v5, 2, v10
	s_or_b32 s1, s0, s1
	v_lshl_or_b32 v4, v226, 6, v4
	v_and_b32_e32 v5, 32, v5
	v_lshl_or_b32 v229, s3, 5, v3
	v_or_b32_e32 v3, s1, v2
	s_add_i32 s1, s15, 2
	v_bitop3_b32 v6, v4, s4, v5 bitop3:0xde
	s_lshl_b32 s4, s1, 5
	s_or_b32 s0, s0, s4
	s_cmp_gt_i32 s15, 0
	v_bitop3_b32 v228, v4, s5, v5 bitop3:0xde
	v_or_b32_e32 v4, s0, v2
	s_cselect_b64 s[74:75], -1, 0
	s_lshl_b32 s0, s15, 11
	s_lshl_b32 s3, s3, 8
	s_cmp_lt_i32 s15, 3
	s_cselect_b64 s[8:9], -1, 0
	v_writelane_b32 v255, s8, 15
	s_cmp_gt_i32 s15, -2
	v_lshlrev_b32_e32 v230, 6, v2
	v_writelane_b32 v255, s9, 16
	s_cselect_b64 s[8:9], -1, 0
	s_lshl_b32 s1, s1, 11
	v_writelane_b32 v255, s8, 1
	s_cmp_lt_i32 s15, 1
	v_lshlrev_b32_e32 v2, 14, v11
	v_writelane_b32 v255, s9, 2
	s_cselect_b64 s[8:9], -1, 0
	v_writelane_b32 v255, s8, 17
	v_and_b32_e32 v2, 0xffff8000, v2
	v_lshl_add_u32 v2, v12, 11, v2
	v_writelane_b32 v255, s9, 18
	v_readlane_b32 s8, v254, 26
	s_add_i32 s0, s8, s0
	s_add_i32 s0, s0, s3
	v_lshl_add_u32 v238, v3, 6, s8
	v_and_b32_e32 v3, 1, v11
	v_lshl_or_b32 v2, v3, 6, v2
	v_lshl_add_u32 v190, v13, 1, v2
	v_lshlrev_b32_e32 v2, 14, v14
	s_add_i32 s9, s0, 0xfffffc00
	v_add_u32_e32 v240, s0, v230
	s_add_i32 s0, s8, s1
	v_and_b32_e32 v2, 0xffff8000, v2
	s_waitcnt vmcnt(6)
	s_add_i32 s0, s0, s3
	v_lshl_add_u32 v2, v15, 11, v2
	v_and_b32_e32 v3, 1, v14
	v_lshl_or_b32 v227, s15, 6, v226
	v_writelane_b32 v255, s9, 25
	s_add_i32 s1, s0, 0xfffffc00
	v_lshl_or_b32 v2, v3, 6, v2
	v_cmp_eq_u32_e64 s[4:5], 15, v226
	s_mov_b32 s90, 0
	v_cmp_eq_u32_e64 s[6:7], 0, v226
	v_or_b32_e32 v231, 16, v227
	v_or_b32_e32 v232, 32, v227
	v_or_b32_e32 v233, 48, v227
	v_add_u32_e32 v234, 0x80, v227
	v_add_u32_e32 v235, 0x90, v227
	v_add_u32_e32 v236, 0xa0, v227
	v_add_u32_e32 v237, 0xb0, v227
	v_lshl_add_u32 v239, v4, 6, s8
	v_writelane_b32 v255, s1, 26
	v_add_u32_e32 v241, s0, v230
	v_mov_b32_e32 v191, v35
	v_lshl_add_u32 v192, v16, 1, v2
	v_mov_b32_e32 v193, v35
	v_add_u32_e32 v242, 0, v6
	s_barrier
	s_mov_b32 s100, 0
	s_branch .LBB0_688

; #define PG8_STAGE(bufoff, gbase, voff) do { _Pragma("unroll") for (int _i = 0; _i < 2; ++_i) \
;         __builtin_amdgcn_global_load_lds((const unsigned*)((const char*)(gbase) + (voff)[_i]), (PG8_LAS unsigned*)(lds + (bufoff) + ldsw + _i * 8192), 16, 0, 0); } while (0)
; #define PG8_LDA(dst, b, h) do { _Pragma("unroll") for (int m = 0; m < 4; ++m) _Pragma("unroll") for (int k = 0; k < 2; ++k) dst[m][k] = *(const PG8_LAS bf16x8*)(lds + PG8_SA(b, h) + aoff + m * 2048 + k * 1024); } while (0)
; #define PG8_LDB(dst, b, h) do { _Pragma("unroll") for (int n = 0; n < 2; ++n) _Pragma("unroll") for (int k = 0; k < 2; ++k) dst[n][k] = *(const PG8_LAS bf16x8*)(lds + PG8_SB(b, h) + boff + n * 2048 + k * 1024); } while (0)
; #define PG8_MMA(ai, bj, At, Bt) do { __builtin_amdgcn_s_setprio(1); _Pragma("unroll") for (int m = 0; m < 4; ++m) _Pragma("unroll") for (int n = 0; n < 2; ++n) _Pragma("unroll") for (int k = 0; k < 2; ++k) \
;         acc[ai][bj][m][n] = __builtin_amdgcn_mfma_f32_16x16x32_bf16(Bt[n][k], At[m][k], acc[ai][bj][m][n], 0, 0, 0); __builtin_amdgcn_s_setprio(0); } while (0)
; #define PG8_WAIT_V(n) asm volatile("s_waitcnt vmcnt(" #n ")" ::: "memory")
; #define PG8_WAIT_L(n) asm volatile("s_waitcnt lgkmcnt(" #n ")" ::: "memory")
; #define PG8_BAR __builtin_amdgcn_s_barrier()
; #define PG8_SCHED __builtin_amdgcn_sched_barrier(0)
; template <class Epi, class Sched, bool ALIGN_EPI = false, bool SP2 = false>
; __device__ __forceinline__ void gemm_phase(PG8_LAS unsigned char* lds, const Gemm g, const Sched& S, const Epi& E) {
;     ...
;             PG8_LDB(B0, 0, 0); PG8_LDB(B1, 0, 1); PG8_SCHED; PG8_LDA(At, 0, 0); PG8_STAGE(PG8_SA(1, 1), a1 + hstep, voffA);
;             PG8_WAIT_V(8); PG8_WAIT_L(0); PG8_BAR; PG8_MMA(0, 0, At, B0); PG8_MMA(0, 1, At, B1); PG8_BAR; PG8_SCHED;
;             PG8_LDA(At, 0, 1); PG8_STAGE(PG8_SB(0, 0), b2, voffB); PG8_STAGE(PG8_SB(0, 1), b2 + hstep, voffB); PG8_STAGE(PG8_SA(0, 0), a2, voffA);
;             PG8_WAIT_V(8); PG8_WAIT_L(0); PG8_BAR; PG8_MMA(1, 0, At, B0); PG8_MMA(1, 1, At, B1); PG8_BAR; PG8_SCHED;
.LBB0_697:
	s_add_u32 s10, s0, 0xfffc0080
	s_addc_u32 s11, s1, -1
	s_add_i32 s19, 0, 0x10000
	s_cmp_eq_u32 s17, 12
	s_cselect_b32 s13, s95, s11
	s_cselect_b32 s12, s94, s10
	v_add_u32_e32 v38, s19, v228
	s_cselect_b32 s11, s3, s16
	s_cselect_b32 s10, s14, s15
	s_add_i32 s22, 0, 0x14000
	ds_read_b128 v[106:109], v38
	ds_read_b128 v[110:113], v38 offset:1024
	ds_read_b128 v[114:117], v38 offset:2048
	ds_read_b128 v[118:121], v38 offset:3072
	v_add_u32_e32 v38, s22, v228
	ds_read_b128 v[122:125], v38
	ds_read_b128 v[126:129], v38 offset:1024
	ds_read_b128 v[130:133], v38 offset:2048
	ds_read_b128 v[134:137], v38 offset:3072
	v_lshl_add_u64 v[202:203], s[0:1], 0, v[190:191]
	s_add_i32 m0, s80, 0xc000
	ds_read_b128 v[170:173], v242
	ds_read_b128 v[174:177], v242 offset:1024
	ds_read_b128 v[178:181], v242 offset:2048
	ds_read_b128 v[194:197], v242 offset:3072
	ds_read_b128 v[198:201], v242 offset:4096
	ds_read_b128 v[208:211], v242 offset:5120
	ds_read_b128 v[218:221], v242 offset:6144
	ds_read_b128 v[244:247], v242 offset:7168
	global_load_lds_dwordx4 v[202:203], off
	v_lshl_add_u64 v[202:203], s[0:1], 0, v[192:193]
	s_add_i32 m0, s80, 0xe000
	s_nop 0
	global_load_lds_dwordx4 v[202:203], off
	s_cmp_eq_u32 s100, 1
	s_cbranch_scc1 .Lupw1_first
	s_waitcnt vmcnt(8)
.Lupw1_back:
	s_waitcnt lgkmcnt(0)
	s_barrier
	s_setprio 1
	s_waitcnt lgkmcnt(0)
	v_mfma_f32_16x16x32_bf16 v[166:169], v[106:109], v[170:173], v[166:169]
	v_mfma_f32_16x16x32_bf16 v[70:73], v[114:117], v[170:173], v[70:73]
	v_mfma_f32_16x16x32_bf16 v[158:161], v[106:109], v[178:181], v[158:161]
	v_mfma_f32_16x16x32_bf16 v[62:65], v[114:117], v[178:181], v[62:65]
	v_mfma_f32_16x16x32_bf16 v[150:153], v[106:109], v[198:201], v[150:153]
	v_mfma_f32_16x16x32_bf16 v[54:57], v[114:117], v[198:201], v[54:57]
	v_mfma_f32_16x16x32_bf16 v[142:145], v[106:109], v[218:221], v[142:145]
	v_mfma_f32_16x16x32_bf16 v[46:49], v[114:117], v[218:221], v[46:49]
	v_mfma_f32_16x16x32_bf16 v[166:169], v[110:113], v[174:177], v[166:169]
	v_mfma_f32_16x16x32_bf16 v[70:73], v[118:121], v[174:177], v[70:73]
	v_mfma_f32_16x16x32_bf16 v[158:161], v[110:113], v[194:197], v[158:161]
	v_mfma_f32_16x16x32_bf16 v[62:65], v[118:121], v[194:197], v[62:65]
	v_mfma_f32_16x16x32_bf16 v[150:153], v[110:113], v[208:211], v[150:153]
	v_mfma_f32_16x16x32_bf16 v[54:57], v[118:121], v[208:211], v[54:57]
	v_mfma_f32_16x16x32_bf16 v[142:145], v[110:113], v[244:247], v[142:145]
	v_mfma_f32_16x16x32_bf16 v[46:49], v[118:121], v[244:247], v[46:49]
	s_setprio 0
	s_setprio 1
	v_mfma_f32_16x16x32_bf16 v[162:165], v[122:125], v[170:173], v[162:165]
	v_mfma_f32_16x16x32_bf16 v[66:69], v[130:133], v[170:173], v[66:69]
	v_mfma_f32_16x16x32_bf16 v[154:157], v[122:125], v[178:181], v[154:157]
	v_mfma_f32_16x16x32_bf16 v[58:61], v[130:133], v[178:181], v[58:61]
	v_mfma_f32_16x16x32_bf16 v[146:149], v[122:125], v[198:201], v[146:149]
	v_mfma_f32_16x16x32_bf16 v[50:53], v[130:133], v[198:201], v[50:53]
	v_mfma_f32_16x16x32_bf16 v[138:141], v[122:125], v[218:221], v[138:141]
	v_mfma_f32_16x16x32_bf16 v[42:45], v[130:133], v[218:221], v[42:45]
	v_mfma_f32_16x16x32_bf16 v[162:165], v[126:129], v[174:177], v[162:165]
	v_mfma_f32_16x16x32_bf16 v[66:69], v[134:137], v[174:177], v[66:69]
	v_mfma_f32_16x16x32_bf16 v[154:157], v[126:129], v[194:197], v[154:157]
	v_mfma_f32_16x16x32_bf16 v[58:61], v[134:137], v[194:197], v[58:61]
	v_mfma_f32_16x16x32_bf16 v[146:149], v[126:129], v[208:211], v[146:149]
	v_mfma_f32_16x16x32_bf16 v[50:53], v[134:137], v[208:211], v[50:53]
	v_mfma_f32_16x16x32_bf16 v[138:141], v[126:129], v[244:247], v[138:141]
	v_mfma_f32_16x16x32_bf16 v[42:45], v[134:137], v[244:247], v[42:45]
	s_setprio 0
	s_barrier
	s_add_i32 s19, s19, s59
	v_lshl_add_u64 v[202:203], s[10:11], 0, v[34:35]
	s_mov_b32 m0, s19
	ds_read_b128 v[170:173], v242 offset:16384
	ds_read_b128 v[174:177], v242 offset:17408
	ds_read_b128 v[178:181], v242 offset:18432
	ds_read_b128 v[194:197], v242 offset:19456
	ds_read_b128 v[198:201], v242 offset:20480
	ds_read_b128 v[208:211], v242 offset:21504
	ds_read_b128 v[218:221], v242 offset:22528
	ds_read_b128 v[244:247], v242 offset:23552
	global_load_lds_dwordx4 v[202:203], off
	s_add_i32 m0, s19, 0x2000
	s_add_u32 s20, s10, 0x40000
	v_lshl_add_u64 v[212:213], s[10:11], 0, v[188:189]
	s_addc_u32 s21, s11, 0
	s_add_i32 s19, s22, s59
	global_load_lds_dwordx4 v[212:213], off
	v_lshl_add_u64 v[248:249], s[20:21], 0, v[34:35]
	s_mov_b32 m0, s19
	v_lshl_add_u64 v[250:251], s[12:13], 0, v[186:187]
	global_load_lds_dwordx4 v[248:249], off
	v_lshl_add_u64 v[248:249], s[20:21], 0, v[188:189]
	s_add_i32 m0, s19, 0x2000
	s_nop 0
	global_load_lds_dwordx4 v[248:249], off
	v_lshl_add_u64 v[248:249], s[12:13], 0, v[36:37]
	s_mov_b32 m0, s80
	s_nop 0
	global_load_lds_dwordx4 v[248:249], off
	s_mov_b32 m0, s81
	s_nop 0
	global_load_lds_dwordx4 v[250:251], off
	s_cmp_eq_u32 s100, 1
	s_cbranch_scc1 .Lupw2_first
	s_waitcnt vmcnt(8)
; #define PG8_STAGE(bufoff, gbase, voff) do { _Pragma("unroll") for (int _i = 0; _i < 2; ++_i) \
;         __builtin_amdgcn_global_load_lds((const unsigned*)((const char*)(gbase) + (voff)[_i]), (PG8_LAS unsigned*)(lds + (bufoff) + ldsw + _i * 8192), 16, 0, 0); } while (0)
; #define PG8_LDA(dst, b, h) do { _Pragma("unroll") for (int m = 0; m < 4; ++m) _Pragma("unroll") for (int k = 0; k < 2; ++k) dst[m][k] = *(const PG8_LAS bf16x8*)(lds + PG8_SA(b, h) + aoff + m * 2048 + k * 1024); } while (0)
; #define PG8_LDB(dst, b, h) do { _Pragma("unroll") for (int n = 0; n < 2; ++n) _Pragma("unroll") for (int k = 0; k < 2; ++k) dst[n][k] = *(const PG8_LAS bf16x8*)(lds + PG8_SB(b, h) + boff + n * 2048 + k * 1024); } while (0)
; #define PG8_MMA(ai, bj, At, Bt) do { __builtin_amdgcn_s_setprio(1); _Pragma("unroll") for (int m = 0; m < 4; ++m) _Pragma("unroll") for (int n = 0; n < 2; ++n) _Pragma("unroll") for (int k = 0; k < 2; ++k) \
;         acc[ai][bj][m][n] = __builtin_amdgcn_mfma_f32_16x16x32_bf16(Bt[n][k], At[m][k], acc[ai][bj][m][n], 0, 0, 0); __builtin_amdgcn_s_setprio(0); } while (0)
; #define PG8_WAIT_V(n) asm volatile("s_waitcnt vmcnt(" #n ")" ::: "memory")
; #define PG8_WAIT_L(n) asm volatile("s_waitcnt lgkmcnt(" #n ")" ::: "memory")
; #define PG8_BAR __builtin_amdgcn_s_barrier()
; #define PG8_SCHED __builtin_amdgcn_sched_barrier(0)
; template <class Epi, class Sched, bool ALIGN_EPI = false, bool SP2 = false>
; __device__ __forceinline__ void gemm_phase(PG8_LAS unsigned char* lds, const Gemm g, const Sched& S, const Epi& E) {
;     ...
;             PG8_WAIT_V(8); PG8_WAIT_L(0); PG8_BAR; PG8_MMA(1, 0, At, B0); PG8_MMA(1, 1, At, B1); PG8_BAR; PG8_SCHED;
;             PG8_LDB(B0, 1, 0); PG8_LDB(B1, 1, 1); PG8_SCHED; PG8_LDA(At, 1, 0); PG8_STAGE(PG8_SA(0, 1), a2 + hstep, voffA);
;             PG8_WAIT_V(8); PG8_WAIT_L(0); PG8_BAR; PG8_MMA(0, 0, At, B0); PG8_MMA(0, 1, At, B1); PG8_BAR; PG8_SCHED;
.Lupw2_back:
	s_waitcnt lgkmcnt(0)
	s_barrier
	s_setprio 1
	s_waitcnt lgkmcnt(0)
	v_mfma_f32_16x16x32_bf16 v[102:105], v[106:109], v[170:173], v[102:105]
	v_mfma_f32_16x16x32_bf16 v[30:33], v[114:117], v[170:173], v[30:33]
	v_mfma_f32_16x16x32_bf16 v[94:97], v[106:109], v[178:181], v[94:97]
	v_mfma_f32_16x16x32_bf16 v[22:25], v[114:117], v[178:181], v[22:25]
	v_mfma_f32_16x16x32_bf16 v[86:89], v[106:109], v[198:201], v[86:89]
	v_mfma_f32_16x16x32_bf16 v[14:17], v[114:117], v[198:201], v[14:17]
	v_mfma_f32_16x16x32_bf16 v[78:81], v[106:109], v[218:221], v[78:81]
	v_mfma_f32_16x16x32_bf16 v[6:9], v[114:117], v[218:221], v[6:9]
	v_mfma_f32_16x16x32_bf16 v[102:105], v[110:113], v[174:177], v[102:105]
	v_mfma_f32_16x16x32_bf16 v[30:33], v[118:121], v[174:177], v[30:33]
	v_mfma_f32_16x16x32_bf16 v[94:97], v[110:113], v[194:197], v[94:97]
	v_mfma_f32_16x16x32_bf16 v[22:25], v[118:121], v[194:197], v[22:25]
	v_mfma_f32_16x16x32_bf16 v[86:89], v[110:113], v[208:211], v[86:89]
	v_mfma_f32_16x16x32_bf16 v[14:17], v[118:121], v[208:211], v[14:17]
	v_mfma_f32_16x16x32_bf16 v[78:81], v[110:113], v[244:247], v[78:81]
	v_mfma_f32_16x16x32_bf16 v[6:9], v[118:121], v[244:247], v[6:9]
	s_setprio 0
	s_setprio 1
	v_mfma_f32_16x16x32_bf16 v[98:101], v[122:125], v[170:173], v[98:101]
	v_mfma_f32_16x16x32_bf16 v[26:29], v[130:133], v[170:173], v[26:29]
	v_mfma_f32_16x16x32_bf16 v[90:93], v[122:125], v[178:181], v[90:93]
	v_mfma_f32_16x16x32_bf16 v[18:21], v[130:133], v[178:181], v[18:21]
	v_mfma_f32_16x16x32_bf16 v[82:85], v[122:125], v[198:201], v[82:85]
	v_mfma_f32_16x16x32_bf16 v[10:13], v[130:133], v[198:201], v[10:13]
	v_mfma_f32_16x16x32_bf16 v[74:77], v[122:125], v[218:221], v[74:77]
	v_mfma_f32_16x16x32_bf16 v[2:5], v[130:133], v[218:221], v[2:5]
	v_mfma_f32_16x16x32_bf16 v[98:101], v[126:129], v[174:177], v[98:101]
	v_mfma_f32_16x16x32_bf16 v[26:29], v[134:137], v[174:177], v[26:29]
	v_mfma_f32_16x16x32_bf16 v[90:93], v[126:129], v[194:197], v[90:93]
	v_mfma_f32_16x16x32_bf16 v[18:21], v[134:137], v[194:197], v[18:21]
	v_mfma_f32_16x16x32_bf16 v[82:85], v[126:129], v[208:211], v[82:85]
	v_mfma_f32_16x16x32_bf16 v[10:13], v[134:137], v[208:211], v[10:13]
	v_mfma_f32_16x16x32_bf16 v[74:77], v[126:129], v[244:247], v[74:77]
	v_mfma_f32_16x16x32_bf16 v[2:5], v[134:137], v[244:247], v[2:5]
	s_setprio 0
	s_barrier
	s_add_i32 s19, 0, 0x18000
	v_add_u32_e32 v38, s19, v228
	s_add_i32 s20, 0, 0x1c000
	ds_read_b128 v[106:109], v38
	ds_read_b128 v[110:113], v38 offset:1024
	ds_read_b128 v[114:117], v38 offset:2048
	ds_read_b128 v[118:121], v38 offset:3072
	v_add_u32_e32 v38, s20, v228
	ds_read_b128 v[122:125], v38
	ds_read_b128 v[126:129], v38 offset:1024
	ds_read_b128 v[130:133], v38 offset:2048
	ds_read_b128 v[134:137], v38 offset:3072
	s_add_u32 s12, s12, 0x40000
	s_addc_u32 s13, s13, 0
	s_mov_b32 m0, s76
	v_lshl_add_u64 v[38:39], s[12:13], 0, v[36:37]
	ds_read_b128 v[170:173], v242 offset:32768
	ds_read_b128 v[174:177], v242 offset:33792
	ds_read_b128 v[178:181], v242 offset:34816
	ds_read_b128 v[194:197], v242 offset:35840
	ds_read_b128 v[198:201], v242 offset:36864
	ds_read_b128 v[208:211], v242 offset:37888
	ds_read_b128 v[218:221], v242 offset:38912
	ds_read_b128 v[244:247], v242 offset:39936
	global_load_lds_dwordx4 v[38:39], off
	v_lshl_add_u64 v[38:39], s[12:13], 0, v[186:187]
	s_mov_b32 m0, s77
	s_nop 0
	global_load_lds_dwordx4 v[38:39], off
	s_waitcnt vmcnt(8)
	s_waitcnt lgkmcnt(0)
	s_barrier
	s_setprio 1
	s_waitcnt lgkmcnt(0)
	v_mfma_f32_16x16x32_bf16 v[166:169], v[106:109], v[170:173], v[166:169]
	v_mfma_f32_16x16x32_bf16 v[70:73], v[114:117], v[170:173], v[70:73]
	v_mfma_f32_16x16x32_bf16 v[158:161], v[106:109], v[178:181], v[158:161]
	v_mfma_f32_16x16x32_bf16 v[62:65], v[114:117], v[178:181], v[62:65]
	v_mfma_f32_16x16x32_bf16 v[150:153], v[106:109], v[198:201], v[150:153]
	v_mfma_f32_16x16x32_bf16 v[54:57], v[114:117], v[198:201], v[54:57]
	v_mfma_f32_16x16x32_bf16 v[142:145], v[106:109], v[218:221], v[142:145]
	v_mfma_f32_16x16x32_bf16 v[46:49], v[114:117], v[218:221], v[46:49]
	v_mfma_f32_16x16x32_bf16 v[166:169], v[110:113], v[174:177], v[166:169]
	v_mfma_f32_16x16x32_bf16 v[70:73], v[118:121], v[174:177], v[70:73]
	v_mfma_f32_16x16x32_bf16 v[158:161], v[110:113], v[194:197], v[158:161]
	v_mfma_f32_16x16x32_bf16 v[62:65], v[118:121], v[194:197], v[62:65]
	v_mfma_f32_16x16x32_bf16 v[150:153], v[110:113], v[208:211], v[150:153]
	v_mfma_f32_16x16x32_bf16 v[54:57], v[118:121], v[208:211], v[54:57]
	v_mfma_f32_16x16x32_bf16 v[142:145], v[110:113], v[244:247], v[142:145]
	v_mfma_f32_16x16x32_bf16 v[46:49], v[118:121], v[244:247], v[46:49]
	s_setprio 0
	s_setprio 1
	v_mfma_f32_16x16x32_bf16 v[162:165], v[122:125], v[170:173], v[162:165]
	v_mfma_f32_16x16x32_bf16 v[66:69], v[130:133], v[170:173], v[66:69]
	v_mfma_f32_16x16x32_bf16 v[154:157], v[122:125], v[178:181], v[154:157]
	v_mfma_f32_16x16x32_bf16 v[58:61], v[130:133], v[178:181], v[58:61]
	v_mfma_f32_16x16x32_bf16 v[146:149], v[122:125], v[198:201], v[146:149]
	v_mfma_f32_16x16x32_bf16 v[50:53], v[130:133], v[198:201], v[50:53]
	v_mfma_f32_16x16x32_bf16 v[138:141], v[122:125], v[218:221], v[138:141]
	v_mfma_f32_16x16x32_bf16 v[42:45], v[130:133], v[218:221], v[42:45]
	v_mfma_f32_16x16x32_bf16 v[162:165], v[126:129], v[174:177], v[162:165]
	v_mfma_f32_16x16x32_bf16 v[66:69], v[134:137], v[174:177], v[66:69]
	v_mfma_f32_16x16x32_bf16 v[154:157], v[126:129], v[194:197], v[154:157]
	v_mfma_f32_16x16x32_bf16 v[58:61], v[134:137], v[194:197], v[58:61]
	v_mfma_f32_16x16x32_bf16 v[146:149], v[126:129], v[208:211], v[146:149]
	v_mfma_f32_16x16x32_bf16 v[50:53], v[134:137], v[208:211], v[50:53]
	v_mfma_f32_16x16x32_bf16 v[138:141], v[126:129], v[244:247], v[138:141]
	v_mfma_f32_16x16x32_bf16 v[42:45], v[134:137], v[244:247], v[42:45]
	s_setprio 0
	s_barrier
; #define PG8_STAGE(bufoff, gbase, voff) do { _Pragma("unroll") for (int _i = 0; _i < 2; ++_i) \
;         __builtin_amdgcn_global_load_lds((const unsigned*)((const char*)(gbase) + (voff)[_i]), (PG8_LAS unsigned*)(lds + (bufoff) + ldsw + _i * 8192), 16, 0, 0); } while (0)
; #define PG8_LDA(dst, b, h) do { _Pragma("unroll") for (int m = 0; m < 4; ++m) _Pragma("unroll") for (int k = 0; k < 2; ++k) dst[m][k] = *(const PG8_LAS bf16x8*)(lds + PG8_SA(b, h) + aoff + m * 2048 + k * 1024); } while (0)
; #define PG8_MMA(ai, bj, At, Bt) do { __builtin_amdgcn_s_setprio(1); _Pragma("unroll") for (int m = 0; m < 4; ++m) _Pragma("unroll") for (int n = 0; n < 2; ++n) _Pragma("unroll") for (int k = 0; k < 2; ++k) \
;         acc[ai][bj][m][n] = __builtin_amdgcn_mfma_f32_16x16x32_bf16(Bt[n][k], At[m][k], acc[ai][bj][m][n], 0, 0, 0); __builtin_amdgcn_s_setprio(0); } while (0)
; #define PG8_WAIT_V(n) asm volatile("s_waitcnt vmcnt(" #n ")" ::: "memory")
; #define PG8_WAIT_L(n) asm volatile("s_waitcnt lgkmcnt(" #n ")" ::: "memory")
; #define PG8_BAR __builtin_amdgcn_s_barrier()
; #define PG8_SCHED __builtin_amdgcn_sched_barrier(0)
; template <class Epi, class Sched, bool ALIGN_EPI = false, bool SP2 = false>
; __device__ __forceinline__ void gemm_phase(PG8_LAS unsigned char* lds, const Gemm g, const Sched& S, const Epi& E) {
;     ...
;         for (int t = 0; t < nt; t += 2) {
;             const bool last = (t == nt - 2);
;             const char* a1 = cA + (size_t)(t + 1) * kstep;
;             const char* a2 = last ? nA : cA + (size_t)(t + 2) * kstep; const char* b2 = last ? nB : cB + (size_t)(t + 2) * kstep;
;             const char* a3 = a2 + kstep; const char* b3 = b2 + kstep;
;             if (last && has_next) S.a_ready(nxt);
;     ...
;             PG8_LDA(At, 1, 1); PG8_STAGE(PG8_SB(1, 0), b3, voffB); PG8_STAGE(PG8_SB(1, 1), b3 + hstep, voffB); PG8_STAGE(PG8_SA(1, 0), a3, voffA);
;             PG8_WAIT_V(8); PG8_WAIT_L(0); PG8_BAR; PG8_MMA(1, 0, At, B0); PG8_MMA(1, 1, At, B1); PG8_BAR; PG8_SCHED;
	s_add_i32 s12, s19, s59
	v_lshl_add_u64 v[38:39], v[202:203], 0, s[70:71]
	s_mov_b32 m0, s12
	ds_read_b128 v[170:173], v242 offset:49152
	ds_read_b128 v[174:177], v242 offset:50176
	ds_read_b128 v[178:181], v242 offset:51200
	ds_read_b128 v[194:197], v242 offset:52224
	ds_read_b128 v[198:201], v242 offset:53248
	ds_read_b128 v[208:211], v242 offset:54272
	ds_read_b128 v[218:221], v242 offset:55296
	ds_read_b128 v[244:247], v242 offset:56320
	global_load_lds_dwordx4 v[38:39], off
	s_add_i32 m0, s12, 0x2000
	s_add_u32 s10, s10, 0x40080
	v_lshl_add_u64 v[38:39], v[212:213], 0, s[70:71]
	s_addc_u32 s11, s11, 0
	s_add_i32 s12, s20, s59
	global_load_lds_dwordx4 v[38:39], off
	v_lshl_add_u64 v[38:39], s[10:11], 0, v[34:35]
	s_mov_b32 m0, s12
	s_nop 0
	global_load_lds_dwordx4 v[38:39], off
	v_lshl_add_u64 v[38:39], s[10:11], 0, v[188:189]
	s_add_i32 m0, s12, 0x2000
	s_nop 0
	global_load_lds_dwordx4 v[38:39], off
	v_lshl_add_u64 v[38:39], v[248:249], 0, s[70:71]
	s_mov_b32 m0, s82
	s_nop 0
	global_load_lds_dwordx4 v[38:39], off
	v_lshl_add_u64 v[38:39], v[250:251], 0, s[70:71]
	s_mov_b32 m0, s83
	s_nop 0
	global_load_lds_dwordx4 v[38:39], off
	s_waitcnt vmcnt(8)
	s_waitcnt lgkmcnt(0)
	s_barrier
	s_setprio 1
	s_waitcnt lgkmcnt(0)
	v_mfma_f32_16x16x32_bf16 v[102:105], v[106:109], v[170:173], v[102:105]
	v_mfma_f32_16x16x32_bf16 v[30:33], v[114:117], v[170:173], v[30:33]
	v_mfma_f32_16x16x32_bf16 v[94:97], v[106:109], v[178:181], v[94:97]
	v_mfma_f32_16x16x32_bf16 v[22:25], v[114:117], v[178:181], v[22:25]
	v_mfma_f32_16x16x32_bf16 v[86:89], v[106:109], v[198:201], v[86:89]
	v_mfma_f32_16x16x32_bf16 v[14:17], v[114:117], v[198:201], v[14:17]
	v_mfma_f32_16x16x32_bf16 v[78:81], v[106:109], v[218:221], v[78:81]
	v_mfma_f32_16x16x32_bf16 v[6:9], v[114:117], v[218:221], v[6:9]
	v_mfma_f32_16x16x32_bf16 v[102:105], v[110:113], v[174:177], v[102:105]
	v_mfma_f32_16x16x32_bf16 v[30:33], v[118:121], v[174:177], v[30:33]
	v_mfma_f32_16x16x32_bf16 v[94:97], v[110:113], v[194:197], v[94:97]
	v_mfma_f32_16x16x32_bf16 v[22:25], v[118:121], v[194:197], v[22:25]
	v_mfma_f32_16x16x32_bf16 v[86:89], v[110:113], v[208:211], v[86:89]
	v_mfma_f32_16x16x32_bf16 v[14:17], v[118:121], v[208:211], v[14:17]
	v_mfma_f32_16x16x32_bf16 v[78:81], v[110:113], v[244:247], v[78:81]
	v_mfma_f32_16x16x32_bf16 v[6:9], v[118:121], v[244:247], v[6:9]
	s_setprio 0
	s_setprio 1
	v_mfma_f32_16x16x32_bf16 v[98:101], v[122:125], v[170:173], v[98:101]
	v_mfma_f32_16x16x32_bf16 v[26:29], v[130:133], v[170:173], v[26:29]
	v_mfma_f32_16x16x32_bf16 v[90:93], v[122:125], v[178:181], v[90:93]
	v_mfma_f32_16x16x32_bf16 v[18:21], v[130:133], v[178:181], v[18:21]
	v_mfma_f32_16x16x32_bf16 v[82:85], v[122:125], v[198:201], v[82:85]
	v_mfma_f32_16x16x32_bf16 v[10:13], v[130:133], v[198:201], v[10:13]
	v_mfma_f32_16x16x32_bf16 v[74:77], v[122:125], v[218:221], v[74:77]
	v_mfma_f32_16x16x32_bf16 v[2:5], v[130:133], v[218:221], v[2:5]
	v_mfma_f32_16x16x32_bf16 v[98:101], v[126:129], v[174:177], v[98:101]
	v_mfma_f32_16x16x32_bf16 v[26:29], v[134:137], v[174:177], v[26:29]
	v_mfma_f32_16x16x32_bf16 v[90:93], v[126:129], v[194:197], v[90:93]
	v_mfma_f32_16x16x32_bf16 v[18:21], v[134:137], v[194:197], v[18:21]
	v_mfma_f32_16x16x32_bf16 v[82:85], v[126:129], v[208:211], v[82:85]
	v_mfma_f32_16x16x32_bf16 v[10:13], v[134:137], v[208:211], v[10:13]
	v_mfma_f32_16x16x32_bf16 v[74:77], v[126:129], v[244:247], v[74:77]
	v_mfma_f32_16x16x32_bf16 v[2:5], v[134:137], v[244:247], v[2:5]
	s_setprio 0
	s_barrier
	s_add_i32 s17, s17, 2
	s_add_u32 s0, s0, 0x100
	s_addc_u32 s1, s1, 0
	s_add_u32 s15, s15, 0x100
	s_addc_u32 s16, s16, 0
	s_cmp_gt_u32 s17, 13
	s_cbranch_scc0 .LBB0_697
	v_readlane_b32 s0, v255, 13
	v_readlane_b32 s1, v255, 14
	s_and_b64 vcc, exec, s[0:1]
	s_cbranch_vccz .LBB0_702
	s_barrier
	s_cmpk_gt_i32 s18, 0x83
	s_mov_b64 s[0:1], -1
	s_cbranch_scc1 .LBB0_703

; #define PG8_MMA(ai, bj, At, Bt) do { __builtin_amdgcn_s_setprio(1); _Pragma("unroll") for (int m = 0; m < 4; ++m) _Pragma("unroll") for (int n = 0; n < 2; ++n) _Pragma("unroll") for (int k = 0; k < 2; ++k) \
;         acc[ai][bj][m][n] = __builtin_amdgcn_mfma_f32_16x16x32_bf16(Bt[n][k], At[m][k], acc[ai][bj][m][n], 0, 0, 0); __builtin_amdgcn_s_setprio(0); } while (0)
; #define PG8_WAIT_V(n) asm volatile("s_waitcnt vmcnt(" #n ")" ::: "memory")
; #define PG8_WAIT_L(n) asm volatile("s_waitcnt lgkmcnt(" #n ")" ::: "memory")
; #define PG8_BAR __builtin_amdgcn_s_barrier()
; #define PG8_SCHED __builtin_amdgcn_sched_barrier(0)
; template <class Epi, class Sched, bool ALIGN_EPI = false, bool SP2 = false>
; __device__ __forceinline__ void gemm_phase(PG8_LAS unsigned char* lds, const Gemm g, const Sched& S, const Epi& E) {
;     ...
;             PG8_WAIT_V(8); PG8_WAIT_L(0); PG8_BAR; PG8_MMA(0, 0, At, B0); PG8_MMA(0, 1, At, B1); PG8_BAR; PG8_SCHED;
;     ...
;             PG8_WAIT_V(8); PG8_WAIT_L(0); PG8_BAR; PG8_MMA(1, 0, At, B0); PG8_MMA(1, 1, At, B1); PG8_BAR; PG8_SCHED;
.Lupw1_first:
	s_waitcnt vmcnt(24)
	s_branch .Lupw1_back
.Lupw2_first:
	s_waitcnt vmcnt(24)
	s_mov_b32 s100, 0
	s_branch .Lupw2_back

; template <class Epi, class Sched, bool ALIGN_EPI = false, bool SP2 = false>
; __device__ __forceinline__ void gemm_phase(PG8_LAS unsigned char* lds, const Gemm g, const Sched& S, const Epi& E) {
;     ...
;         if constexpr (!Epi::AFTER_DRAIN) { E(acc, cur, wr, wc, fr, fq); S.done(cur); }
;         if (!has_next) break;
.Lec_done:
	s_mov_b32 s100, 1
	s_mov_b64 s[2:3], exec
